# scan pass 2 main-loop loads (a, b, gate x: last use) system-scope nontemporal so the stream does not evict the attention K/V tiles from L2
# speedup vs baseline: 1.0120x; 1.0120x over previous
; DEV unsigned pack2(float a, float b) { float2v v = {a, b}; return __builtin_bit_cast(unsigned, __builtin_convertvector(v, bf16x2v)); }
; DEV float bflo(unsigned u) { return __uint_as_float(u << 16); }
; DEV float bfhi(unsigned u) { return __uint_as_float(u & 0xffff0000u); }
; DEV float gelu_exact(float v) { return 0.5f * v * (1.f + erff(v * 0.7071067811865476f)); }
; DEV void ph_scan2(const Params& p, int item) {
;     ...
; #pragma unroll 8
;   for (int t = 0; t < CHL; ++t) {
;     float4 a = *(const float4*)(p.a_arr + (row0 + t) * 1024 + ch);
;     float4 bb = *(const float4*)(p.b_arr + (row0 + t) * 1024 + ch);
;     u32x2 xg = *(const u32x2*)(p.z + (row0 + t) * ZLD + CXG + ch);
;     H[0] = a.x * H[0] + bb.x; H[1] = a.y * H[1] + bb.y; H[2] = a.z * H[2] + bb.z; H[3] = a.w * H[3] + bb.w;
;     u32x2 pk;
;     pk[0] = pack2(gelu_exact(bflo(xg[0])) * H[0], gelu_exact(bfhi(xg[0])) * H[1]);
;     pk[1] = pack2(gelu_exact(bflo(xg[1])) * H[2], gelu_exact(bfhi(xg[1])) * H[3]);
;     *(u32x2*)(p.orn + (row0 + t) * 1024 + ch) = pk;
;   }
.Lsc_main:
	global_load_dwordx4 v[80:83], v1, s[2:3] sc0 sc1 nt
	global_load_dwordx4 v[84:87], v1, s[4:5] sc0 sc1 nt
	global_load_dwordx2 v[88:89], v2, s[6:7] sc0 sc1 nt
	s_add_u32 s2, s2, 0x1000
	s_addc_u32 s3, s3, 0
	s_add_u32 s4, s4, 0x1000
	s_addc_u32 s5, s5, 0
	s_add_u32 s6, s6, 0x2500
	s_addc_u32 s7, s7, 0
	global_load_dwordx4 v[90:93], v1, s[2:3] sc0 sc1 nt
	global_load_dwordx4 v[94:97], v1, s[4:5] sc0 sc1 nt
	global_load_dwordx2 v[98:99], v2, s[6:7] sc0 sc1 nt
	s_add_u32 s2, s2, 0x1000
	s_addc_u32 s3, s3, 0
	s_add_u32 s4, s4, 0x1000
	s_addc_u32 s5, s5, 0
	s_add_u32 s6, s6, 0x2500
	s_addc_u32 s7, s7, 0
	global_load_dwordx4 v[100:103], v1, s[2:3] sc0 sc1 nt
	global_load_dwordx4 v[104:107], v1, s[4:5] sc0 sc1 nt
	global_load_dwordx2 v[108:109], v2, s[6:7] sc0 sc1 nt
	s_add_u32 s2, s2, 0x1000
	s_addc_u32 s3, s3, 0
	s_add_u32 s4, s4, 0x1000
	s_addc_u32 s5, s5, 0
	s_add_u32 s6, s6, 0x2500
	s_addc_u32 s7, s7, 0
	global_load_dwordx4 v[110:113], v1, s[2:3] sc0 sc1 nt
	global_load_dwordx4 v[114:117], v1, s[4:5] sc0 sc1 nt
	global_load_dwordx2 v[118:119], v2, s[6:7] sc0 sc1 nt
	s_add_u32 s2, s2, 0x1000
	s_addc_u32 s3, s3, 0
	s_add_u32 s4, s4, 0x1000
	s_addc_u32 s5, s5, 0
	s_add_u32 s6, s6, 0x2500
	s_addc_u32 s7, s7, 0
	global_load_dwordx4 v[120:123], v1, s[2:3] sc0 sc1 nt
	global_load_dwordx4 v[124:127], v1, s[4:5] sc0 sc1 nt
	global_load_dwordx2 v[128:129], v2, s[6:7] sc0 sc1 nt
	s_add_u32 s2, s2, 0x1000
	s_addc_u32 s3, s3, 0
	s_add_u32 s4, s4, 0x1000
	s_addc_u32 s5, s5, 0
	s_add_u32 s6, s6, 0x2500
	s_addc_u32 s7, s7, 0
	global_load_dwordx4 v[130:133], v1, s[2:3] sc0 sc1 nt
	global_load_dwordx4 v[134:137], v1, s[4:5] sc0 sc1 nt
	global_load_dwordx2 v[138:139], v2, s[6:7] sc0 sc1 nt
	s_add_u32 s2, s2, 0x1000
	s_addc_u32 s3, s3, 0
	s_add_u32 s4, s4, 0x1000
	s_addc_u32 s5, s5, 0
	s_add_u32 s6, s6, 0x2500
	s_addc_u32 s7, s7, 0
	global_load_dwordx4 v[140:143], v1, s[2:3] sc0 sc1 nt
	global_load_dwordx4 v[144:147], v1, s[4:5] sc0 sc1 nt
	global_load_dwordx2 v[148:149], v2, s[6:7] sc0 sc1 nt
	s_add_u32 s2, s2, 0x1000
	s_addc_u32 s3, s3, 0
	s_add_u32 s4, s4, 0x1000
	s_addc_u32 s5, s5, 0
	s_add_u32 s6, s6, 0x2500
	s_addc_u32 s7, s7, 0
	global_load_dwordx4 v[150:153], v1, s[2:3] sc0 sc1 nt
	global_load_dwordx4 v[154:157], v1, s[4:5] sc0 sc1 nt
	global_load_dwordx2 v[158:159], v2, s[6:7] sc0 sc1 nt
	s_add_u32 s2, s2, 0x1000
	s_addc_u32 s3, s3, 0
	s_add_u32 s4, s4, 0x1000
	s_addc_u32 s5, s5, 0
	s_add_u32 s6, s6, 0x2500
	s_addc_u32 s7, s7, 0
	s_waitcnt vmcnt(21)
	v_fma_f32 v4, v80, v4, v84
	v_fma_f32 v5, v81, v5, v85
	v_fma_f32 v6, v82, v6, v86
	v_fma_f32 v7, v83, v7, v87
	v_lshlrev_b32_e32 v168, 16, v88
	v_and_b32_e32 v169, 0xffff0000, v88
	v_lshlrev_b32_e32 v170, 16, v89
	v_and_b32_e32 v171, 0xffff0000, v89
	v_mul_f32_e32 v160, 0x3f3504f3, v168
	v_mul_f32_e32 v161, v160, v160
	v_fmamk_f32 v162, v161, 0xba1345e1, v8
	v_fmaak_f32 v162, v161, v162, 0xbcdac9b8
	v_fmaak_f32 v162, v161, v162, 0x3de703be
	v_fmaak_f32 v162, v161, v162, 0xbec09330
	v_fmaak_f32 v161, v161, v162, 0x3e0375d0
	v_fma_f32 v165, |v160|, v161, |v160|
	v_fma_f32 v161, |v160|, s72, v9
	v_fma_f32 v161, |v160|, v161, s73
	v_fma_f32 v161, |v160|, v161, s74
	v_fma_f32 v161, |v160|, v161, s75
	v_fma_f32 v161, |v160|, v161, s76
	v_fma_f32 v161, |v160|, v161, s77
	v_fma_f32 v161, |v160|, v161, |v160|
	v_mul_f32_e32 v162, 0xbfb8aa3b, v161
	v_fma_f32 v163, v161, s78, -v162
	v_rndne_f32_e32 v164, v162
	v_fmac_f32_e32 v163, 0xb2a5705f, v161
	v_sub_f32_e32 v162, v162, v164
	v_add_f32_e32 v162, v162, v163
	v_cvt_i32_f32_e32 v163, v164
	v_exp_f32_e32 v162, v162
	v_cmp_nlt_f32_e32 vcc, s79, v161
	v_ldexp_f32 v162, v162, v163
	s_nop 0
	v_cndmask_b32_e32 v162, 0, v162, vcc
	v_cmp_ngt_f32_e32 vcc, s80, v161
	s_nop 1
	v_cndmask_b32_e32 v161, v3, v162, vcc
	v_sub_f32_e32 v166, 1.0, v161
	v_cmp_lt_f32_e64 vcc, |v160|, 1.0
	s_nop 1
	v_cndmask_b32_e32 v165, v166, v165, vcc
	v_bfi_b32 v165, s81, v165, v160
	v_mul_f32_e32 v161, 0.5, v168
	v_add_f32_e32 v165, 1.0, v165
	v_mul_f32_e32 v161, v161, v165
	v_mul_f32_e32 v176, v161, v4
	v_mul_f32_e32 v160, 0x3f3504f3, v169
	v_mul_f32_e32 v161, v160, v160
	v_fmamk_f32 v162, v161, 0xba1345e1, v8
	v_fmaak_f32 v162, v161, v162, 0xbcdac9b8
	v_fmaak_f32 v162, v161, v162, 0x3de703be
	v_fmaak_f32 v162, v161, v162, 0xbec09330
	v_fmaak_f32 v161, v161, v162, 0x3e0375d0
	v_fma_f32 v165, |v160|, v161, |v160|
	v_fma_f32 v161, |v160|, s72, v9
	v_fma_f32 v161, |v160|, v161, s73
	v_fma_f32 v161, |v160|, v161, s74
	v_fma_f32 v161, |v160|, v161, s75
	v_fma_f32 v161, |v160|, v161, s76
	v_fma_f32 v161, |v160|, v161, s77
	v_fma_f32 v161, |v160|, v161, |v160|
	v_mul_f32_e32 v162, 0xbfb8aa3b, v161
	v_fma_f32 v163, v161, s78, -v162
	v_rndne_f32_e32 v164, v162
	v_fmac_f32_e32 v163, 0xb2a5705f, v161
	v_sub_f32_e32 v162, v162, v164
	v_add_f32_e32 v162, v162, v163
	v_cvt_i32_f32_e32 v163, v164
	v_exp_f32_e32 v162, v162
	v_cmp_nlt_f32_e32 vcc, s79, v161
	v_ldexp_f32 v162, v162, v163
	s_nop 0
	v_cndmask_b32_e32 v162, 0, v162, vcc
	v_cmp_ngt_f32_e32 vcc, s80, v161
	s_nop 1
	v_cndmask_b32_e32 v161, v3, v162, vcc
	v_sub_f32_e32 v166, 1.0, v161
	v_cmp_lt_f32_e64 vcc, |v160|, 1.0
	s_nop 1
	v_cndmask_b32_e32 v165, v166, v165, vcc
	v_bfi_b32 v165, s81, v165, v160
	v_mul_f32_e32 v161, 0.5, v169
	v_add_f32_e32 v165, 1.0, v165
	v_mul_f32_e32 v161, v161, v165
	v_mul_f32_e32 v177, v161, v5
	v_mul_f32_e32 v160, 0x3f3504f3, v170
	v_mul_f32_e32 v161, v160, v160
	v_fmamk_f32 v162, v161, 0xba1345e1, v8
	v_fmaak_f32 v162, v161, v162, 0xbcdac9b8
	v_fmaak_f32 v162, v161, v162, 0x3de703be
	v_fmaak_f32 v162, v161, v162, 0xbec09330
	v_fmaak_f32 v161, v161, v162, 0x3e0375d0
	v_fma_f32 v165, |v160|, v161, |v160|
; DEV unsigned pack2(float a, float b) { float2v v = {a, b}; return __builtin_bit_cast(unsigned, __builtin_convertvector(v, bf16x2v)); }
; DEV float bflo(unsigned u) { return __uint_as_float(u << 16); }
; DEV float bfhi(unsigned u) { return __uint_as_float(u & 0xffff0000u); }
; DEV float gelu_exact(float v) { return 0.5f * v * (1.f + erff(v * 0.7071067811865476f)); }
; DEV void ph_scan2(const Params& p, int item) {
;     ...
; #pragma unroll 8
;   for (int t = 0; t < CHL; ++t) {
;     float4 a = *(const float4*)(p.a_arr + (row0 + t) * 1024 + ch);
;     float4 bb = *(const float4*)(p.b_arr + (row0 + t) * 1024 + ch);
;     u32x2 xg = *(const u32x2*)(p.z + (row0 + t) * ZLD + CXG + ch);
;     H[0] = a.x * H[0] + bb.x; H[1] = a.y * H[1] + bb.y; H[2] = a.z * H[2] + bb.z; H[3] = a.w * H[3] + bb.w;
;     u32x2 pk;
;     pk[0] = pack2(gelu_exact(bflo(xg[0])) * H[0], gelu_exact(bfhi(xg[0])) * H[1]);
;     pk[1] = pack2(gelu_exact(bflo(xg[1])) * H[2], gelu_exact(bfhi(xg[1])) * H[3]);
;     *(u32x2*)(p.orn + (row0 + t) * 1024 + ch) = pk;
;   }
	v_fma_f32 v161, |v160|, s72, v9
	v_fma_f32 v161, |v160|, v161, s73
	v_fma_f32 v161, |v160|, v161, s74
	v_fma_f32 v161, |v160|, v161, s75
	v_fma_f32 v161, |v160|, v161, s76
	v_fma_f32 v161, |v160|, v161, s77
	v_fma_f32 v161, |v160|, v161, |v160|
	v_mul_f32_e32 v162, 0xbfb8aa3b, v161
	v_fma_f32 v163, v161, s78, -v162
	v_rndne_f32_e32 v164, v162
	v_fmac_f32_e32 v163, 0xb2a5705f, v161
	v_sub_f32_e32 v162, v162, v164
	v_add_f32_e32 v162, v162, v163
	v_cvt_i32_f32_e32 v163, v164
	v_exp_f32_e32 v162, v162
	v_cmp_nlt_f32_e32 vcc, s79, v161
	v_ldexp_f32 v162, v162, v163
	s_nop 0
	v_cndmask_b32_e32 v162, 0, v162, vcc
	v_cmp_ngt_f32_e32 vcc, s80, v161
	s_nop 1
	v_cndmask_b32_e32 v161, v3, v162, vcc
	v_sub_f32_e32 v166, 1.0, v161
	v_cmp_lt_f32_e64 vcc, |v160|, 1.0
	s_nop 1
	v_cndmask_b32_e32 v165, v166, v165, vcc
	v_bfi_b32 v165, s81, v165, v160
	v_mul_f32_e32 v161, 0.5, v170
	v_add_f32_e32 v165, 1.0, v165
	v_mul_f32_e32 v161, v161, v165
	v_mul_f32_e32 v178, v161, v6
	v_mul_f32_e32 v160, 0x3f3504f3, v171
	v_mul_f32_e32 v161, v160, v160
	v_fmamk_f32 v162, v161, 0xba1345e1, v8
	v_fmaak_f32 v162, v161, v162, 0xbcdac9b8
	v_fmaak_f32 v162, v161, v162, 0x3de703be
	v_fmaak_f32 v162, v161, v162, 0xbec09330
	v_fmaak_f32 v161, v161, v162, 0x3e0375d0
	v_fma_f32 v165, |v160|, v161, |v160|
	v_fma_f32 v161, |v160|, s72, v9
	v_fma_f32 v161, |v160|, v161, s73
	v_fma_f32 v161, |v160|, v161, s74
	v_fma_f32 v161, |v160|, v161, s75
	v_fma_f32 v161, |v160|, v161, s76
	v_fma_f32 v161, |v160|, v161, s77
	v_fma_f32 v161, |v160|, v161, |v160|
	v_mul_f32_e32 v162, 0xbfb8aa3b, v161
	v_fma_f32 v163, v161, s78, -v162
	v_rndne_f32_e32 v164, v162
	v_fmac_f32_e32 v163, 0xb2a5705f, v161
	v_sub_f32_e32 v162, v162, v164
	v_add_f32_e32 v162, v162, v163
	v_cvt_i32_f32_e32 v163, v164
	v_exp_f32_e32 v162, v162
	v_cmp_nlt_f32_e32 vcc, s79, v161
	v_ldexp_f32 v162, v162, v163
	s_nop 0
	v_cndmask_b32_e32 v162, 0, v162, vcc
	v_cmp_ngt_f32_e32 vcc, s80, v161
	s_nop 1
	v_cndmask_b32_e32 v161, v3, v162, vcc
	v_sub_f32_e32 v166, 1.0, v161
	v_cmp_lt_f32_e64 vcc, |v160|, 1.0
	s_nop 1
	v_cndmask_b32_e32 v165, v166, v165, vcc
	v_bfi_b32 v165, s81, v165, v160
	v_mul_f32_e32 v161, 0.5, v171
	v_add_f32_e32 v165, 1.0, v165
	v_mul_f32_e32 v161, v161, v165
	v_mul_f32_e32 v179, v161, v7
	v_cvt_pk_bf16_f32 v180, v176, v177
	v_cvt_pk_bf16_f32 v181, v178, v179
	global_store_dwordx2 v2, v[180:181], s[34:35]
	s_add_u32 s34, s34, 0x800
	s_addc_u32 s35, s35, 0
	s_waitcnt vmcnt(19)
	v_fma_f32 v4, v90, v4, v94
	v_fma_f32 v5, v91, v5, v95
	v_fma_f32 v6, v92, v6, v96
	v_fma_f32 v7, v93, v7, v97
	v_lshlrev_b32_e32 v168, 16, v98
	v_and_b32_e32 v169, 0xffff0000, v98
	v_lshlrev_b32_e32 v170, 16, v99
	v_and_b32_e32 v171, 0xffff0000, v99
	v_mul_f32_e32 v160, 0x3f3504f3, v168
	v_mul_f32_e32 v161, v160, v160
	v_fmamk_f32 v162, v161, 0xba1345e1, v8
	v_fmaak_f32 v162, v161, v162, 0xbcdac9b8
	v_fmaak_f32 v162, v161, v162, 0x3de703be
	v_fmaak_f32 v162, v161, v162, 0xbec09330
	v_fmaak_f32 v161, v161, v162, 0x3e0375d0
	v_fma_f32 v165, |v160|, v161, |v160|
	v_fma_f32 v161, |v160|, s72, v9
	v_fma_f32 v161, |v160|, v161, s73
	v_fma_f32 v161, |v160|, v161, s74
	v_fma_f32 v161, |v160|, v161, s75
	v_fma_f32 v161, |v160|, v161, s76
	v_fma_f32 v161, |v160|, v161, s77
	v_fma_f32 v161, |v160|, v161, |v160|
	v_mul_f32_e32 v162, 0xbfb8aa3b, v161
	v_fma_f32 v163, v161, s78, -v162
	v_rndne_f32_e32 v164, v162
	v_fmac_f32_e32 v163, 0xb2a5705f, v161
	v_sub_f32_e32 v162, v162, v164
	v_add_f32_e32 v162, v162, v163
	v_cvt_i32_f32_e32 v163, v164
	v_exp_f32_e32 v162, v162
	v_cmp_nlt_f32_e32 vcc, s79, v161
	v_ldexp_f32 v162, v162, v163
	s_nop 0
	v_cndmask_b32_e32 v162, 0, v162, vcc
	v_cmp_ngt_f32_e32 vcc, s80, v161
	s_nop 1
	v_cndmask_b32_e32 v161, v3, v162, vcc
	v_sub_f32_e32 v166, 1.0, v161
	v_cmp_lt_f32_e64 vcc, |v160|, 1.0
	s_nop 1
	v_cndmask_b32_e32 v165, v166, v165, vcc
	v_bfi_b32 v165, s81, v165, v160
	v_mul_f32_e32 v161, 0.5, v168
	v_add_f32_e32 v165, 1.0, v165
	v_mul_f32_e32 v161, v161, v165
	v_mul_f32_e32 v176, v161, v4
	v_mul_f32_e32 v160, 0x3f3504f3, v169
	v_mul_f32_e32 v161, v160, v160
	v_fmamk_f32 v162, v161, 0xba1345e1, v8
	v_fmaak_f32 v162, v161, v162, 0xbcdac9b8
	v_fmaak_f32 v162, v161, v162, 0x3de703be
	v_fmaak_f32 v162, v161, v162, 0xbec09330
	v_fmaak_f32 v161, v161, v162, 0x3e0375d0
	v_fma_f32 v165, |v160|, v161, |v160|
	v_fma_f32 v161, |v160|, s72, v9
	v_fma_f32 v161, |v160|, v161, s73
	v_fma_f32 v161, |v160|, v161, s74
	v_fma_f32 v161, |v160|, v161, s75
	v_fma_f32 v161, |v160|, v161, s76
	v_fma_f32 v161, |v160|, v161, s77
	v_fma_f32 v161, |v160|, v161, |v160|
	v_mul_f32_e32 v162, 0xbfb8aa3b, v161
	v_fma_f32 v163, v161, s78, -v162
	v_rndne_f32_e32 v164, v162
	v_fmac_f32_e32 v163, 0xb2a5705f, v161
	v_sub_f32_e32 v162, v162, v164
	v_add_f32_e32 v162, v162, v163
	v_cvt_i32_f32_e32 v163, v164
	v_exp_f32_e32 v162, v162
	v_cmp_nlt_f32_e32 vcc, s79, v161
	v_ldexp_f32 v162, v162, v163
	s_nop 0
	v_cndmask_b32_e32 v162, 0, v162, vcc
	v_cmp_ngt_f32_e32 vcc, s80, v161
	s_nop 1
	v_cndmask_b32_e32 v161, v3, v162, vcc
	v_sub_f32_e32 v166, 1.0, v161
	v_cmp_lt_f32_e64 vcc, |v160|, 1.0
	s_nop 1
	v_cndmask_b32_e32 v165, v166, v165, vcc
	v_bfi_b32 v165, s81, v165, v160
	v_mul_f32_e32 v161, 0.5, v169
	v_add_f32_e32 v165, 1.0, v165
	v_mul_f32_e32 v161, v161, v165
	v_mul_f32_e32 v177, v161, v5
	v_mul_f32_e32 v160, 0x3f3504f3, v170
	v_mul_f32_e32 v161, v160, v160
	v_fmamk_f32 v162, v161, 0xba1345e1, v8
	v_fmaak_f32 v162, v161, v162, 0xbcdac9b8
	v_fmaak_f32 v162, v161, v162, 0x3de703be
	v_fmaak_f32 v162, v161, v162, 0xbec09330
	v_fmaak_f32 v161, v161, v162, 0x3e0375d0
	v_fma_f32 v165, |v160|, v161, |v160|
	v_fma_f32 v161, |v160|, s72, v9
; DEV unsigned pack2(float a, float b) { float2v v = {a, b}; return __builtin_bit_cast(unsigned, __builtin_convertvector(v, bf16x2v)); }
; DEV float bflo(unsigned u) { return __uint_as_float(u << 16); }
; DEV float bfhi(unsigned u) { return __uint_as_float(u & 0xffff0000u); }
; DEV float gelu_exact(float v) { return 0.5f * v * (1.f + erff(v * 0.7071067811865476f)); }
; DEV void ph_scan2(const Params& p, int item) {
;     ...
; #pragma unroll 8
;   for (int t = 0; t < CHL; ++t) {
;     float4 a = *(const float4*)(p.a_arr + (row0 + t) * 1024 + ch);
;     float4 bb = *(const float4*)(p.b_arr + (row0 + t) * 1024 + ch);
;     u32x2 xg = *(const u32x2*)(p.z + (row0 + t) * ZLD + CXG + ch);
;     H[0] = a.x * H[0] + bb.x; H[1] = a.y * H[1] + bb.y; H[2] = a.z * H[2] + bb.z; H[3] = a.w * H[3] + bb.w;
;     u32x2 pk;
;     pk[0] = pack2(gelu_exact(bflo(xg[0])) * H[0], gelu_exact(bfhi(xg[0])) * H[1]);
;     pk[1] = pack2(gelu_exact(bflo(xg[1])) * H[2], gelu_exact(bfhi(xg[1])) * H[3]);
;     *(u32x2*)(p.orn + (row0 + t) * 1024 + ch) = pk;
;   }
	v_fma_f32 v161, |v160|, v161, s73
	v_fma_f32 v161, |v160|, v161, s74
	v_fma_f32 v161, |v160|, v161, s75
	v_fma_f32 v161, |v160|, v161, s76
	v_fma_f32 v161, |v160|, v161, s77
	v_fma_f32 v161, |v160|, v161, |v160|
	v_mul_f32_e32 v162, 0xbfb8aa3b, v161
	v_fma_f32 v163, v161, s78, -v162
	v_rndne_f32_e32 v164, v162
	v_fmac_f32_e32 v163, 0xb2a5705f, v161
	v_sub_f32_e32 v162, v162, v164
	v_add_f32_e32 v162, v162, v163
	v_cvt_i32_f32_e32 v163, v164
	v_exp_f32_e32 v162, v162
	v_cmp_nlt_f32_e32 vcc, s79, v161
	v_ldexp_f32 v162, v162, v163
	s_nop 0
	v_cndmask_b32_e32 v162, 0, v162, vcc
	v_cmp_ngt_f32_e32 vcc, s80, v161
	s_nop 1
	v_cndmask_b32_e32 v161, v3, v162, vcc
	v_sub_f32_e32 v166, 1.0, v161
	v_cmp_lt_f32_e64 vcc, |v160|, 1.0
	s_nop 1
	v_cndmask_b32_e32 v165, v166, v165, vcc
	v_bfi_b32 v165, s81, v165, v160
	v_mul_f32_e32 v161, 0.5, v170
	v_add_f32_e32 v165, 1.0, v165
	v_mul_f32_e32 v161, v161, v165
	v_mul_f32_e32 v178, v161, v6
	v_mul_f32_e32 v160, 0x3f3504f3, v171
	v_mul_f32_e32 v161, v160, v160
	v_fmamk_f32 v162, v161, 0xba1345e1, v8
	v_fmaak_f32 v162, v161, v162, 0xbcdac9b8
	v_fmaak_f32 v162, v161, v162, 0x3de703be
	v_fmaak_f32 v162, v161, v162, 0xbec09330
	v_fmaak_f32 v161, v161, v162, 0x3e0375d0
	v_fma_f32 v165, |v160|, v161, |v160|
	v_fma_f32 v161, |v160|, s72, v9
	v_fma_f32 v161, |v160|, v161, s73
	v_fma_f32 v161, |v160|, v161, s74
	v_fma_f32 v161, |v160|, v161, s75
	v_fma_f32 v161, |v160|, v161, s76
	v_fma_f32 v161, |v160|, v161, s77
	v_fma_f32 v161, |v160|, v161, |v160|
	v_mul_f32_e32 v162, 0xbfb8aa3b, v161
	v_fma_f32 v163, v161, s78, -v162
	v_rndne_f32_e32 v164, v162
	v_fmac_f32_e32 v163, 0xb2a5705f, v161
	v_sub_f32_e32 v162, v162, v164
	v_add_f32_e32 v162, v162, v163
	v_cvt_i32_f32_e32 v163, v164
	v_exp_f32_e32 v162, v162
	v_cmp_nlt_f32_e32 vcc, s79, v161
	v_ldexp_f32 v162, v162, v163
	s_nop 0
	v_cndmask_b32_e32 v162, 0, v162, vcc
	v_cmp_ngt_f32_e32 vcc, s80, v161
	s_nop 1
	v_cndmask_b32_e32 v161, v3, v162, vcc
	v_sub_f32_e32 v166, 1.0, v161
	v_cmp_lt_f32_e64 vcc, |v160|, 1.0
	s_nop 1
	v_cndmask_b32_e32 v165, v166, v165, vcc
	v_bfi_b32 v165, s81, v165, v160
	v_mul_f32_e32 v161, 0.5, v171
	v_add_f32_e32 v165, 1.0, v165
	v_mul_f32_e32 v161, v161, v165
	v_mul_f32_e32 v179, v161, v7
	v_cvt_pk_bf16_f32 v180, v176, v177
	v_cvt_pk_bf16_f32 v181, v178, v179
	global_store_dwordx2 v2, v[180:181], s[34:35]
	s_add_u32 s34, s34, 0x800
	s_addc_u32 s35, s35, 0
	s_waitcnt vmcnt(17)
	v_fma_f32 v4, v100, v4, v104
	v_fma_f32 v5, v101, v5, v105
	v_fma_f32 v6, v102, v6, v106
	v_fma_f32 v7, v103, v7, v107
	v_lshlrev_b32_e32 v168, 16, v108
	v_and_b32_e32 v169, 0xffff0000, v108
	v_lshlrev_b32_e32 v170, 16, v109
	v_and_b32_e32 v171, 0xffff0000, v109
	v_mul_f32_e32 v160, 0x3f3504f3, v168
	v_mul_f32_e32 v161, v160, v160
	v_fmamk_f32 v162, v161, 0xba1345e1, v8
	v_fmaak_f32 v162, v161, v162, 0xbcdac9b8
	v_fmaak_f32 v162, v161, v162, 0x3de703be
	v_fmaak_f32 v162, v161, v162, 0xbec09330
	v_fmaak_f32 v161, v161, v162, 0x3e0375d0
	v_fma_f32 v165, |v160|, v161, |v160|
	v_fma_f32 v161, |v160|, s72, v9
	v_fma_f32 v161, |v160|, v161, s73
	v_fma_f32 v161, |v160|, v161, s74
	v_fma_f32 v161, |v160|, v161, s75
	v_fma_f32 v161, |v160|, v161, s76
	v_fma_f32 v161, |v160|, v161, s77
	v_fma_f32 v161, |v160|, v161, |v160|
	v_mul_f32_e32 v162, 0xbfb8aa3b, v161
	v_fma_f32 v163, v161, s78, -v162
	v_rndne_f32_e32 v164, v162
	v_fmac_f32_e32 v163, 0xb2a5705f, v161
	v_sub_f32_e32 v162, v162, v164
	v_add_f32_e32 v162, v162, v163
	v_cvt_i32_f32_e32 v163, v164
	v_exp_f32_e32 v162, v162
	v_cmp_nlt_f32_e32 vcc, s79, v161
	v_ldexp_f32 v162, v162, v163
	s_nop 0
	v_cndmask_b32_e32 v162, 0, v162, vcc
	v_cmp_ngt_f32_e32 vcc, s80, v161
	s_nop 1
	v_cndmask_b32_e32 v161, v3, v162, vcc
	v_sub_f32_e32 v166, 1.0, v161
	v_cmp_lt_f32_e64 vcc, |v160|, 1.0
	s_nop 1
	v_cndmask_b32_e32 v165, v166, v165, vcc
	v_bfi_b32 v165, s81, v165, v160
	v_mul_f32_e32 v161, 0.5, v168
	v_add_f32_e32 v165, 1.0, v165
	v_mul_f32_e32 v161, v161, v165
	v_mul_f32_e32 v176, v161, v4
	v_mul_f32_e32 v160, 0x3f3504f3, v169
	v_mul_f32_e32 v161, v160, v160
	v_fmamk_f32 v162, v161, 0xba1345e1, v8
	v_fmaak_f32 v162, v161, v162, 0xbcdac9b8
	v_fmaak_f32 v162, v161, v162, 0x3de703be
	v_fmaak_f32 v162, v161, v162, 0xbec09330
	v_fmaak_f32 v161, v161, v162, 0x3e0375d0
	v_fma_f32 v165, |v160|, v161, |v160|
	v_fma_f32 v161, |v160|, s72, v9
	v_fma_f32 v161, |v160|, v161, s73
	v_fma_f32 v161, |v160|, v161, s74
	v_fma_f32 v161, |v160|, v161, s75
	v_fma_f32 v161, |v160|, v161, s76
	v_fma_f32 v161, |v160|, v161, s77
	v_fma_f32 v161, |v160|, v161, |v160|
	v_mul_f32_e32 v162, 0xbfb8aa3b, v161
	v_fma_f32 v163, v161, s78, -v162
	v_rndne_f32_e32 v164, v162
	v_fmac_f32_e32 v163, 0xb2a5705f, v161
	v_sub_f32_e32 v162, v162, v164
	v_add_f32_e32 v162, v162, v163
	v_cvt_i32_f32_e32 v163, v164
	v_exp_f32_e32 v162, v162
	v_cmp_nlt_f32_e32 vcc, s79, v161
	v_ldexp_f32 v162, v162, v163
	s_nop 0
	v_cndmask_b32_e32 v162, 0, v162, vcc
	v_cmp_ngt_f32_e32 vcc, s80, v161
	s_nop 1
	v_cndmask_b32_e32 v161, v3, v162, vcc
	v_sub_f32_e32 v166, 1.0, v161
	v_cmp_lt_f32_e64 vcc, |v160|, 1.0
	s_nop 1
	v_cndmask_b32_e32 v165, v166, v165, vcc
	v_bfi_b32 v165, s81, v165, v160
	v_mul_f32_e32 v161, 0.5, v169
	v_add_f32_e32 v165, 1.0, v165
	v_mul_f32_e32 v161, v161, v165
	v_mul_f32_e32 v177, v161, v5
	v_mul_f32_e32 v160, 0x3f3504f3, v170
	v_mul_f32_e32 v161, v160, v160
	v_fmamk_f32 v162, v161, 0xba1345e1, v8
	v_fmaak_f32 v162, v161, v162, 0xbcdac9b8
	v_fmaak_f32 v162, v161, v162, 0x3de703be
	v_fmaak_f32 v162, v161, v162, 0xbec09330
	v_fmaak_f32 v161, v161, v162, 0x3e0375d0
	v_fma_f32 v165, |v160|, v161, |v160|
	v_fma_f32 v161, |v160|, s72, v9
	v_fma_f32 v161, |v160|, v161, s73
; DEV unsigned pack2(float a, float b) { float2v v = {a, b}; return __builtin_bit_cast(unsigned, __builtin_convertvector(v, bf16x2v)); }
; DEV float bflo(unsigned u) { return __uint_as_float(u << 16); }
; DEV float bfhi(unsigned u) { return __uint_as_float(u & 0xffff0000u); }
; DEV float gelu_exact(float v) { return 0.5f * v * (1.f + erff(v * 0.7071067811865476f)); }
; DEV void ph_scan2(const Params& p, int item) {
;     ...
; #pragma unroll 8
;   for (int t = 0; t < CHL; ++t) {
;     float4 a = *(const float4*)(p.a_arr + (row0 + t) * 1024 + ch);
;     float4 bb = *(const float4*)(p.b_arr + (row0 + t) * 1024 + ch);
;     u32x2 xg = *(const u32x2*)(p.z + (row0 + t) * ZLD + CXG + ch);
;     H[0] = a.x * H[0] + bb.x; H[1] = a.y * H[1] + bb.y; H[2] = a.z * H[2] + bb.z; H[3] = a.w * H[3] + bb.w;
;     u32x2 pk;
;     pk[0] = pack2(gelu_exact(bflo(xg[0])) * H[0], gelu_exact(bfhi(xg[0])) * H[1]);
;     pk[1] = pack2(gelu_exact(bflo(xg[1])) * H[2], gelu_exact(bfhi(xg[1])) * H[3]);
;     *(u32x2*)(p.orn + (row0 + t) * 1024 + ch) = pk;
;   }
	v_fma_f32 v161, |v160|, v161, s74
	v_fma_f32 v161, |v160|, v161, s75
	v_fma_f32 v161, |v160|, v161, s76
	v_fma_f32 v161, |v160|, v161, s77
	v_fma_f32 v161, |v160|, v161, |v160|
	v_mul_f32_e32 v162, 0xbfb8aa3b, v161
	v_fma_f32 v163, v161, s78, -v162
	v_rndne_f32_e32 v164, v162
	v_fmac_f32_e32 v163, 0xb2a5705f, v161
	v_sub_f32_e32 v162, v162, v164
	v_add_f32_e32 v162, v162, v163
	v_cvt_i32_f32_e32 v163, v164
	v_exp_f32_e32 v162, v162
	v_cmp_nlt_f32_e32 vcc, s79, v161
	v_ldexp_f32 v162, v162, v163
	s_nop 0
	v_cndmask_b32_e32 v162, 0, v162, vcc
	v_cmp_ngt_f32_e32 vcc, s80, v161
	s_nop 1
	v_cndmask_b32_e32 v161, v3, v162, vcc
	v_sub_f32_e32 v166, 1.0, v161
	v_cmp_lt_f32_e64 vcc, |v160|, 1.0
	s_nop 1
	v_cndmask_b32_e32 v165, v166, v165, vcc
	v_bfi_b32 v165, s81, v165, v160
	v_mul_f32_e32 v161, 0.5, v170
	v_add_f32_e32 v165, 1.0, v165
	v_mul_f32_e32 v161, v161, v165
	v_mul_f32_e32 v178, v161, v6
	v_mul_f32_e32 v160, 0x3f3504f3, v171
	v_mul_f32_e32 v161, v160, v160
	v_fmamk_f32 v162, v161, 0xba1345e1, v8
	v_fmaak_f32 v162, v161, v162, 0xbcdac9b8
	v_fmaak_f32 v162, v161, v162, 0x3de703be
	v_fmaak_f32 v162, v161, v162, 0xbec09330
	v_fmaak_f32 v161, v161, v162, 0x3e0375d0
	v_fma_f32 v165, |v160|, v161, |v160|
	v_fma_f32 v161, |v160|, s72, v9
	v_fma_f32 v161, |v160|, v161, s73
	v_fma_f32 v161, |v160|, v161, s74
	v_fma_f32 v161, |v160|, v161, s75
	v_fma_f32 v161, |v160|, v161, s76
	v_fma_f32 v161, |v160|, v161, s77
	v_fma_f32 v161, |v160|, v161, |v160|
	v_mul_f32_e32 v162, 0xbfb8aa3b, v161
	v_fma_f32 v163, v161, s78, -v162
	v_rndne_f32_e32 v164, v162
	v_fmac_f32_e32 v163, 0xb2a5705f, v161
	v_sub_f32_e32 v162, v162, v164
	v_add_f32_e32 v162, v162, v163
	v_cvt_i32_f32_e32 v163, v164
	v_exp_f32_e32 v162, v162
	v_cmp_nlt_f32_e32 vcc, s79, v161
	v_ldexp_f32 v162, v162, v163
	s_nop 0
	v_cndmask_b32_e32 v162, 0, v162, vcc
	v_cmp_ngt_f32_e32 vcc, s80, v161
	s_nop 1
	v_cndmask_b32_e32 v161, v3, v162, vcc
	v_sub_f32_e32 v166, 1.0, v161
	v_cmp_lt_f32_e64 vcc, |v160|, 1.0
	s_nop 1
	v_cndmask_b32_e32 v165, v166, v165, vcc
	v_bfi_b32 v165, s81, v165, v160
	v_mul_f32_e32 v161, 0.5, v171
	v_add_f32_e32 v165, 1.0, v165
	v_mul_f32_e32 v161, v161, v165
	v_mul_f32_e32 v179, v161, v7
	v_cvt_pk_bf16_f32 v180, v176, v177
	v_cvt_pk_bf16_f32 v181, v178, v179
	global_store_dwordx2 v2, v[180:181], s[34:35]
	s_add_u32 s34, s34, 0x800
	s_addc_u32 s35, s35, 0
	s_waitcnt vmcnt(15)
	v_fma_f32 v4, v110, v4, v114
	v_fma_f32 v5, v111, v5, v115
	v_fma_f32 v6, v112, v6, v116
	v_fma_f32 v7, v113, v7, v117
	v_lshlrev_b32_e32 v168, 16, v118
	v_and_b32_e32 v169, 0xffff0000, v118
	v_lshlrev_b32_e32 v170, 16, v119
	v_and_b32_e32 v171, 0xffff0000, v119
	v_mul_f32_e32 v160, 0x3f3504f3, v168
	v_mul_f32_e32 v161, v160, v160
	v_fmamk_f32 v162, v161, 0xba1345e1, v8
	v_fmaak_f32 v162, v161, v162, 0xbcdac9b8
	v_fmaak_f32 v162, v161, v162, 0x3de703be
	v_fmaak_f32 v162, v161, v162, 0xbec09330
	v_fmaak_f32 v161, v161, v162, 0x3e0375d0
	v_fma_f32 v165, |v160|, v161, |v160|
	v_fma_f32 v161, |v160|, s72, v9
	v_fma_f32 v161, |v160|, v161, s73
	v_fma_f32 v161, |v160|, v161, s74
	v_fma_f32 v161, |v160|, v161, s75
	v_fma_f32 v161, |v160|, v161, s76
	v_fma_f32 v161, |v160|, v161, s77
	v_fma_f32 v161, |v160|, v161, |v160|
	v_mul_f32_e32 v162, 0xbfb8aa3b, v161
	v_fma_f32 v163, v161, s78, -v162
	v_rndne_f32_e32 v164, v162
	v_fmac_f32_e32 v163, 0xb2a5705f, v161
	v_sub_f32_e32 v162, v162, v164
	v_add_f32_e32 v162, v162, v163
	v_cvt_i32_f32_e32 v163, v164
	v_exp_f32_e32 v162, v162
	v_cmp_nlt_f32_e32 vcc, s79, v161
	v_ldexp_f32 v162, v162, v163
	s_nop 0
	v_cndmask_b32_e32 v162, 0, v162, vcc
	v_cmp_ngt_f32_e32 vcc, s80, v161
	s_nop 1
	v_cndmask_b32_e32 v161, v3, v162, vcc
	v_sub_f32_e32 v166, 1.0, v161
	v_cmp_lt_f32_e64 vcc, |v160|, 1.0
	s_nop 1
	v_cndmask_b32_e32 v165, v166, v165, vcc
	v_bfi_b32 v165, s81, v165, v160
	v_mul_f32_e32 v161, 0.5, v168
	v_add_f32_e32 v165, 1.0, v165
	v_mul_f32_e32 v161, v161, v165
	v_mul_f32_e32 v176, v161, v4
	v_mul_f32_e32 v160, 0x3f3504f3, v169
	v_mul_f32_e32 v161, v160, v160
	v_fmamk_f32 v162, v161, 0xba1345e1, v8
	v_fmaak_f32 v162, v161, v162, 0xbcdac9b8
	v_fmaak_f32 v162, v161, v162, 0x3de703be
	v_fmaak_f32 v162, v161, v162, 0xbec09330
	v_fmaak_f32 v161, v161, v162, 0x3e0375d0
	v_fma_f32 v165, |v160|, v161, |v160|
	v_fma_f32 v161, |v160|, s72, v9
	v_fma_f32 v161, |v160|, v161, s73
	v_fma_f32 v161, |v160|, v161, s74
	v_fma_f32 v161, |v160|, v161, s75
	v_fma_f32 v161, |v160|, v161, s76
	v_fma_f32 v161, |v160|, v161, s77
	v_fma_f32 v161, |v160|, v161, |v160|
	v_mul_f32_e32 v162, 0xbfb8aa3b, v161
	v_fma_f32 v163, v161, s78, -v162
	v_rndne_f32_e32 v164, v162
	v_fmac_f32_e32 v163, 0xb2a5705f, v161
	v_sub_f32_e32 v162, v162, v164
	v_add_f32_e32 v162, v162, v163
	v_cvt_i32_f32_e32 v163, v164
	v_exp_f32_e32 v162, v162
	v_cmp_nlt_f32_e32 vcc, s79, v161
	v_ldexp_f32 v162, v162, v163
	s_nop 0
	v_cndmask_b32_e32 v162, 0, v162, vcc
	v_cmp_ngt_f32_e32 vcc, s80, v161
	s_nop 1
	v_cndmask_b32_e32 v161, v3, v162, vcc
	v_sub_f32_e32 v166, 1.0, v161
	v_cmp_lt_f32_e64 vcc, |v160|, 1.0
	s_nop 1
	v_cndmask_b32_e32 v165, v166, v165, vcc
	v_bfi_b32 v165, s81, v165, v160
	v_mul_f32_e32 v161, 0.5, v169
	v_add_f32_e32 v165, 1.0, v165
	v_mul_f32_e32 v161, v161, v165
	v_mul_f32_e32 v177, v161, v5
	v_mul_f32_e32 v160, 0x3f3504f3, v170
	v_mul_f32_e32 v161, v160, v160
	v_fmamk_f32 v162, v161, 0xba1345e1, v8
	v_fmaak_f32 v162, v161, v162, 0xbcdac9b8
	v_fmaak_f32 v162, v161, v162, 0x3de703be
	v_fmaak_f32 v162, v161, v162, 0xbec09330
	v_fmaak_f32 v161, v161, v162, 0x3e0375d0
	v_fma_f32 v165, |v160|, v161, |v160|
	v_fma_f32 v161, |v160|, s72, v9
	v_fma_f32 v161, |v160|, v161, s73
	v_fma_f32 v161, |v160|, v161, s74
; DEV unsigned pack2(float a, float b) { float2v v = {a, b}; return __builtin_bit_cast(unsigned, __builtin_convertvector(v, bf16x2v)); }
; DEV float bflo(unsigned u) { return __uint_as_float(u << 16); }
; DEV float bfhi(unsigned u) { return __uint_as_float(u & 0xffff0000u); }
; DEV float gelu_exact(float v) { return 0.5f * v * (1.f + erff(v * 0.7071067811865476f)); }
; DEV void ph_scan2(const Params& p, int item) {
;     ...
; #pragma unroll 8
;   for (int t = 0; t < CHL; ++t) {
;     float4 a = *(const float4*)(p.a_arr + (row0 + t) * 1024 + ch);
;     float4 bb = *(const float4*)(p.b_arr + (row0 + t) * 1024 + ch);
;     u32x2 xg = *(const u32x2*)(p.z + (row0 + t) * ZLD + CXG + ch);
;     H[0] = a.x * H[0] + bb.x; H[1] = a.y * H[1] + bb.y; H[2] = a.z * H[2] + bb.z; H[3] = a.w * H[3] + bb.w;
;     u32x2 pk;
;     pk[0] = pack2(gelu_exact(bflo(xg[0])) * H[0], gelu_exact(bfhi(xg[0])) * H[1]);
;     pk[1] = pack2(gelu_exact(bflo(xg[1])) * H[2], gelu_exact(bfhi(xg[1])) * H[3]);
;     *(u32x2*)(p.orn + (row0 + t) * 1024 + ch) = pk;
;   }
	v_fma_f32 v161, |v160|, v161, s75
	v_fma_f32 v161, |v160|, v161, s76
	v_fma_f32 v161, |v160|, v161, s77
	v_fma_f32 v161, |v160|, v161, |v160|
	v_mul_f32_e32 v162, 0xbfb8aa3b, v161
	v_fma_f32 v163, v161, s78, -v162
	v_rndne_f32_e32 v164, v162
	v_fmac_f32_e32 v163, 0xb2a5705f, v161
	v_sub_f32_e32 v162, v162, v164
	v_add_f32_e32 v162, v162, v163
	v_cvt_i32_f32_e32 v163, v164
	v_exp_f32_e32 v162, v162
	v_cmp_nlt_f32_e32 vcc, s79, v161
	v_ldexp_f32 v162, v162, v163
	s_nop 0
	v_cndmask_b32_e32 v162, 0, v162, vcc
	v_cmp_ngt_f32_e32 vcc, s80, v161
	s_nop 1
	v_cndmask_b32_e32 v161, v3, v162, vcc
	v_sub_f32_e32 v166, 1.0, v161
	v_cmp_lt_f32_e64 vcc, |v160|, 1.0
	s_nop 1
	v_cndmask_b32_e32 v165, v166, v165, vcc
	v_bfi_b32 v165, s81, v165, v160
	v_mul_f32_e32 v161, 0.5, v170
	v_add_f32_e32 v165, 1.0, v165
	v_mul_f32_e32 v161, v161, v165
	v_mul_f32_e32 v178, v161, v6
	v_mul_f32_e32 v160, 0x3f3504f3, v171
	v_mul_f32_e32 v161, v160, v160
	v_fmamk_f32 v162, v161, 0xba1345e1, v8
	v_fmaak_f32 v162, v161, v162, 0xbcdac9b8
	v_fmaak_f32 v162, v161, v162, 0x3de703be
	v_fmaak_f32 v162, v161, v162, 0xbec09330
	v_fmaak_f32 v161, v161, v162, 0x3e0375d0
	v_fma_f32 v165, |v160|, v161, |v160|
	v_fma_f32 v161, |v160|, s72, v9
	v_fma_f32 v161, |v160|, v161, s73
	v_fma_f32 v161, |v160|, v161, s74
	v_fma_f32 v161, |v160|, v161, s75
	v_fma_f32 v161, |v160|, v161, s76
	v_fma_f32 v161, |v160|, v161, s77
	v_fma_f32 v161, |v160|, v161, |v160|
	v_mul_f32_e32 v162, 0xbfb8aa3b, v161
	v_fma_f32 v163, v161, s78, -v162
	v_rndne_f32_e32 v164, v162
	v_fmac_f32_e32 v163, 0xb2a5705f, v161
	v_sub_f32_e32 v162, v162, v164
	v_add_f32_e32 v162, v162, v163
	v_cvt_i32_f32_e32 v163, v164
	v_exp_f32_e32 v162, v162
	v_cmp_nlt_f32_e32 vcc, s79, v161
	v_ldexp_f32 v162, v162, v163
	s_nop 0
	v_cndmask_b32_e32 v162, 0, v162, vcc
	v_cmp_ngt_f32_e32 vcc, s80, v161
	s_nop 1
	v_cndmask_b32_e32 v161, v3, v162, vcc
	v_sub_f32_e32 v166, 1.0, v161
	v_cmp_lt_f32_e64 vcc, |v160|, 1.0
	s_nop 1
	v_cndmask_b32_e32 v165, v166, v165, vcc
	v_bfi_b32 v165, s81, v165, v160
	v_mul_f32_e32 v161, 0.5, v171
	v_add_f32_e32 v165, 1.0, v165
	v_mul_f32_e32 v161, v161, v165
	v_mul_f32_e32 v179, v161, v7
	v_cvt_pk_bf16_f32 v180, v176, v177
	v_cvt_pk_bf16_f32 v181, v178, v179
	global_store_dwordx2 v2, v[180:181], s[34:35]
	s_add_u32 s34, s34, 0x800
	s_addc_u32 s35, s35, 0
	s_waitcnt vmcnt(13)
	v_fma_f32 v4, v120, v4, v124
	v_fma_f32 v5, v121, v5, v125
	v_fma_f32 v6, v122, v6, v126
	v_fma_f32 v7, v123, v7, v127
	v_lshlrev_b32_e32 v168, 16, v128
	v_and_b32_e32 v169, 0xffff0000, v128
	v_lshlrev_b32_e32 v170, 16, v129
	v_and_b32_e32 v171, 0xffff0000, v129
	v_mul_f32_e32 v160, 0x3f3504f3, v168
	v_mul_f32_e32 v161, v160, v160
	v_fmamk_f32 v162, v161, 0xba1345e1, v8
	v_fmaak_f32 v162, v161, v162, 0xbcdac9b8
	v_fmaak_f32 v162, v161, v162, 0x3de703be
	v_fmaak_f32 v162, v161, v162, 0xbec09330
	v_fmaak_f32 v161, v161, v162, 0x3e0375d0
	v_fma_f32 v165, |v160|, v161, |v160|
	v_fma_f32 v161, |v160|, s72, v9
	v_fma_f32 v161, |v160|, v161, s73
	v_fma_f32 v161, |v160|, v161, s74
	v_fma_f32 v161, |v160|, v161, s75
	v_fma_f32 v161, |v160|, v161, s76
	v_fma_f32 v161, |v160|, v161, s77
	v_fma_f32 v161, |v160|, v161, |v160|
	v_mul_f32_e32 v162, 0xbfb8aa3b, v161
	v_fma_f32 v163, v161, s78, -v162
	v_rndne_f32_e32 v164, v162
	v_fmac_f32_e32 v163, 0xb2a5705f, v161
	v_sub_f32_e32 v162, v162, v164
	v_add_f32_e32 v162, v162, v163
	v_cvt_i32_f32_e32 v163, v164
	v_exp_f32_e32 v162, v162
	v_cmp_nlt_f32_e32 vcc, s79, v161
	v_ldexp_f32 v162, v162, v163
	s_nop 0
	v_cndmask_b32_e32 v162, 0, v162, vcc
	v_cmp_ngt_f32_e32 vcc, s80, v161
	s_nop 1
	v_cndmask_b32_e32 v161, v3, v162, vcc
	v_sub_f32_e32 v166, 1.0, v161
	v_cmp_lt_f32_e64 vcc, |v160|, 1.0
	s_nop 1
	v_cndmask_b32_e32 v165, v166, v165, vcc
	v_bfi_b32 v165, s81, v165, v160
	v_mul_f32_e32 v161, 0.5, v168
	v_add_f32_e32 v165, 1.0, v165
	v_mul_f32_e32 v161, v161, v165
	v_mul_f32_e32 v176, v161, v4
	v_mul_f32_e32 v160, 0x3f3504f3, v169
	v_mul_f32_e32 v161, v160, v160
	v_fmamk_f32 v162, v161, 0xba1345e1, v8
	v_fmaak_f32 v162, v161, v162, 0xbcdac9b8
	v_fmaak_f32 v162, v161, v162, 0x3de703be
	v_fmaak_f32 v162, v161, v162, 0xbec09330
	v_fmaak_f32 v161, v161, v162, 0x3e0375d0
	v_fma_f32 v165, |v160|, v161, |v160|
	v_fma_f32 v161, |v160|, s72, v9
	v_fma_f32 v161, |v160|, v161, s73
	v_fma_f32 v161, |v160|, v161, s74
	v_fma_f32 v161, |v160|, v161, s75
	v_fma_f32 v161, |v160|, v161, s76
	v_fma_f32 v161, |v160|, v161, s77
	v_fma_f32 v161, |v160|, v161, |v160|
	v_mul_f32_e32 v162, 0xbfb8aa3b, v161
	v_fma_f32 v163, v161, s78, -v162
	v_rndne_f32_e32 v164, v162
	v_fmac_f32_e32 v163, 0xb2a5705f, v161
	v_sub_f32_e32 v162, v162, v164
	v_add_f32_e32 v162, v162, v163
	v_cvt_i32_f32_e32 v163, v164
	v_exp_f32_e32 v162, v162
	v_cmp_nlt_f32_e32 vcc, s79, v161
	v_ldexp_f32 v162, v162, v163
	s_nop 0
	v_cndmask_b32_e32 v162, 0, v162, vcc
	v_cmp_ngt_f32_e32 vcc, s80, v161
	s_nop 1
	v_cndmask_b32_e32 v161, v3, v162, vcc
	v_sub_f32_e32 v166, 1.0, v161
	v_cmp_lt_f32_e64 vcc, |v160|, 1.0
	s_nop 1
	v_cndmask_b32_e32 v165, v166, v165, vcc
	v_bfi_b32 v165, s81, v165, v160
	v_mul_f32_e32 v161, 0.5, v169
	v_add_f32_e32 v165, 1.0, v165
	v_mul_f32_e32 v161, v161, v165
	v_mul_f32_e32 v177, v161, v5
	v_mul_f32_e32 v160, 0x3f3504f3, v170
	v_mul_f32_e32 v161, v160, v160
	v_fmamk_f32 v162, v161, 0xba1345e1, v8
	v_fmaak_f32 v162, v161, v162, 0xbcdac9b8
	v_fmaak_f32 v162, v161, v162, 0x3de703be
	v_fmaak_f32 v162, v161, v162, 0xbec09330
	v_fmaak_f32 v161, v161, v162, 0x3e0375d0
	v_fma_f32 v165, |v160|, v161, |v160|
	v_fma_f32 v161, |v160|, s72, v9
	v_fma_f32 v161, |v160|, v161, s73
	v_fma_f32 v161, |v160|, v161, s74
	v_fma_f32 v161, |v160|, v161, s75
; DEV unsigned pack2(float a, float b) { float2v v = {a, b}; return __builtin_bit_cast(unsigned, __builtin_convertvector(v, bf16x2v)); }
; DEV float bflo(unsigned u) { return __uint_as_float(u << 16); }
; DEV float bfhi(unsigned u) { return __uint_as_float(u & 0xffff0000u); }
; DEV float gelu_exact(float v) { return 0.5f * v * (1.f + erff(v * 0.7071067811865476f)); }
; DEV void ph_scan2(const Params& p, int item) {
;     ...
; #pragma unroll 8
;   for (int t = 0; t < CHL; ++t) {
;     float4 a = *(const float4*)(p.a_arr + (row0 + t) * 1024 + ch);
;     float4 bb = *(const float4*)(p.b_arr + (row0 + t) * 1024 + ch);
;     u32x2 xg = *(const u32x2*)(p.z + (row0 + t) * ZLD + CXG + ch);
;     H[0] = a.x * H[0] + bb.x; H[1] = a.y * H[1] + bb.y; H[2] = a.z * H[2] + bb.z; H[3] = a.w * H[3] + bb.w;
;     u32x2 pk;
;     pk[0] = pack2(gelu_exact(bflo(xg[0])) * H[0], gelu_exact(bfhi(xg[0])) * H[1]);
;     pk[1] = pack2(gelu_exact(bflo(xg[1])) * H[2], gelu_exact(bfhi(xg[1])) * H[3]);
;     *(u32x2*)(p.orn + (row0 + t) * 1024 + ch) = pk;
;   }
	v_fma_f32 v161, |v160|, v161, s76
	v_fma_f32 v161, |v160|, v161, s77
	v_fma_f32 v161, |v160|, v161, |v160|
	v_mul_f32_e32 v162, 0xbfb8aa3b, v161
	v_fma_f32 v163, v161, s78, -v162
	v_rndne_f32_e32 v164, v162
	v_fmac_f32_e32 v163, 0xb2a5705f, v161
	v_sub_f32_e32 v162, v162, v164
	v_add_f32_e32 v162, v162, v163
	v_cvt_i32_f32_e32 v163, v164
	v_exp_f32_e32 v162, v162
	v_cmp_nlt_f32_e32 vcc, s79, v161
	v_ldexp_f32 v162, v162, v163
	s_nop 0
	v_cndmask_b32_e32 v162, 0, v162, vcc
	v_cmp_ngt_f32_e32 vcc, s80, v161
	s_nop 1
	v_cndmask_b32_e32 v161, v3, v162, vcc
	v_sub_f32_e32 v166, 1.0, v161
	v_cmp_lt_f32_e64 vcc, |v160|, 1.0
	s_nop 1
	v_cndmask_b32_e32 v165, v166, v165, vcc
	v_bfi_b32 v165, s81, v165, v160
	v_mul_f32_e32 v161, 0.5, v170
	v_add_f32_e32 v165, 1.0, v165
	v_mul_f32_e32 v161, v161, v165
	v_mul_f32_e32 v178, v161, v6
	v_mul_f32_e32 v160, 0x3f3504f3, v171
	v_mul_f32_e32 v161, v160, v160
	v_fmamk_f32 v162, v161, 0xba1345e1, v8
	v_fmaak_f32 v162, v161, v162, 0xbcdac9b8
	v_fmaak_f32 v162, v161, v162, 0x3de703be
	v_fmaak_f32 v162, v161, v162, 0xbec09330
	v_fmaak_f32 v161, v161, v162, 0x3e0375d0
	v_fma_f32 v165, |v160|, v161, |v160|
	v_fma_f32 v161, |v160|, s72, v9
	v_fma_f32 v161, |v160|, v161, s73
	v_fma_f32 v161, |v160|, v161, s74
	v_fma_f32 v161, |v160|, v161, s75
	v_fma_f32 v161, |v160|, v161, s76
	v_fma_f32 v161, |v160|, v161, s77
	v_fma_f32 v161, |v160|, v161, |v160|
	v_mul_f32_e32 v162, 0xbfb8aa3b, v161
	v_fma_f32 v163, v161, s78, -v162
	v_rndne_f32_e32 v164, v162
	v_fmac_f32_e32 v163, 0xb2a5705f, v161
	v_sub_f32_e32 v162, v162, v164
	v_add_f32_e32 v162, v162, v163
	v_cvt_i32_f32_e32 v163, v164
	v_exp_f32_e32 v162, v162
	v_cmp_nlt_f32_e32 vcc, s79, v161
	v_ldexp_f32 v162, v162, v163
	s_nop 0
	v_cndmask_b32_e32 v162, 0, v162, vcc
	v_cmp_ngt_f32_e32 vcc, s80, v161
	s_nop 1
	v_cndmask_b32_e32 v161, v3, v162, vcc
	v_sub_f32_e32 v166, 1.0, v161
	v_cmp_lt_f32_e64 vcc, |v160|, 1.0
	s_nop 1
	v_cndmask_b32_e32 v165, v166, v165, vcc
	v_bfi_b32 v165, s81, v165, v160
	v_mul_f32_e32 v161, 0.5, v171
	v_add_f32_e32 v165, 1.0, v165
	v_mul_f32_e32 v161, v161, v165
	v_mul_f32_e32 v179, v161, v7
	v_cvt_pk_bf16_f32 v180, v176, v177
	v_cvt_pk_bf16_f32 v181, v178, v179
	global_store_dwordx2 v2, v[180:181], s[34:35]
	s_add_u32 s34, s34, 0x800
	s_addc_u32 s35, s35, 0
	s_waitcnt vmcnt(11)
	v_fma_f32 v4, v130, v4, v134
	v_fma_f32 v5, v131, v5, v135
	v_fma_f32 v6, v132, v6, v136
	v_fma_f32 v7, v133, v7, v137
	v_lshlrev_b32_e32 v168, 16, v138
	v_and_b32_e32 v169, 0xffff0000, v138
	v_lshlrev_b32_e32 v170, 16, v139
	v_and_b32_e32 v171, 0xffff0000, v139
	v_mul_f32_e32 v160, 0x3f3504f3, v168
	v_mul_f32_e32 v161, v160, v160
	v_fmamk_f32 v162, v161, 0xba1345e1, v8
	v_fmaak_f32 v162, v161, v162, 0xbcdac9b8
	v_fmaak_f32 v162, v161, v162, 0x3de703be
	v_fmaak_f32 v162, v161, v162, 0xbec09330
	v_fmaak_f32 v161, v161, v162, 0x3e0375d0
	v_fma_f32 v165, |v160|, v161, |v160|
	v_fma_f32 v161, |v160|, s72, v9
	v_fma_f32 v161, |v160|, v161, s73
	v_fma_f32 v161, |v160|, v161, s74
	v_fma_f32 v161, |v160|, v161, s75
	v_fma_f32 v161, |v160|, v161, s76
	v_fma_f32 v161, |v160|, v161, s77
	v_fma_f32 v161, |v160|, v161, |v160|
	v_mul_f32_e32 v162, 0xbfb8aa3b, v161
	v_fma_f32 v163, v161, s78, -v162
	v_rndne_f32_e32 v164, v162
	v_fmac_f32_e32 v163, 0xb2a5705f, v161
	v_sub_f32_e32 v162, v162, v164
	v_add_f32_e32 v162, v162, v163
	v_cvt_i32_f32_e32 v163, v164
	v_exp_f32_e32 v162, v162
	v_cmp_nlt_f32_e32 vcc, s79, v161
	v_ldexp_f32 v162, v162, v163
	s_nop 0
	v_cndmask_b32_e32 v162, 0, v162, vcc
	v_cmp_ngt_f32_e32 vcc, s80, v161
	s_nop 1
	v_cndmask_b32_e32 v161, v3, v162, vcc
	v_sub_f32_e32 v166, 1.0, v161
	v_cmp_lt_f32_e64 vcc, |v160|, 1.0
	s_nop 1
	v_cndmask_b32_e32 v165, v166, v165, vcc
	v_bfi_b32 v165, s81, v165, v160
	v_mul_f32_e32 v161, 0.5, v168
	v_add_f32_e32 v165, 1.0, v165
	v_mul_f32_e32 v161, v161, v165
	v_mul_f32_e32 v176, v161, v4
	v_mul_f32_e32 v160, 0x3f3504f3, v169
	v_mul_f32_e32 v161, v160, v160
	v_fmamk_f32 v162, v161, 0xba1345e1, v8
	v_fmaak_f32 v162, v161, v162, 0xbcdac9b8
	v_fmaak_f32 v162, v161, v162, 0x3de703be
	v_fmaak_f32 v162, v161, v162, 0xbec09330
	v_fmaak_f32 v161, v161, v162, 0x3e0375d0
	v_fma_f32 v165, |v160|, v161, |v160|
	v_fma_f32 v161, |v160|, s72, v9
	v_fma_f32 v161, |v160|, v161, s73
	v_fma_f32 v161, |v160|, v161, s74
	v_fma_f32 v161, |v160|, v161, s75
	v_fma_f32 v161, |v160|, v161, s76
	v_fma_f32 v161, |v160|, v161, s77
	v_fma_f32 v161, |v160|, v161, |v160|
	v_mul_f32_e32 v162, 0xbfb8aa3b, v161
	v_fma_f32 v163, v161, s78, -v162
	v_rndne_f32_e32 v164, v162
	v_fmac_f32_e32 v163, 0xb2a5705f, v161
	v_sub_f32_e32 v162, v162, v164
	v_add_f32_e32 v162, v162, v163
	v_cvt_i32_f32_e32 v163, v164
	v_exp_f32_e32 v162, v162
	v_cmp_nlt_f32_e32 vcc, s79, v161
	v_ldexp_f32 v162, v162, v163
	s_nop 0
	v_cndmask_b32_e32 v162, 0, v162, vcc
	v_cmp_ngt_f32_e32 vcc, s80, v161
	s_nop 1
	v_cndmask_b32_e32 v161, v3, v162, vcc
	v_sub_f32_e32 v166, 1.0, v161
	v_cmp_lt_f32_e64 vcc, |v160|, 1.0
	s_nop 1
	v_cndmask_b32_e32 v165, v166, v165, vcc
	v_bfi_b32 v165, s81, v165, v160
	v_mul_f32_e32 v161, 0.5, v169
	v_add_f32_e32 v165, 1.0, v165
	v_mul_f32_e32 v161, v161, v165
	v_mul_f32_e32 v177, v161, v5
	v_mul_f32_e32 v160, 0x3f3504f3, v170
	v_mul_f32_e32 v161, v160, v160
	v_fmamk_f32 v162, v161, 0xba1345e1, v8
	v_fmaak_f32 v162, v161, v162, 0xbcdac9b8
	v_fmaak_f32 v162, v161, v162, 0x3de703be
	v_fmaak_f32 v162, v161, v162, 0xbec09330
	v_fmaak_f32 v161, v161, v162, 0x3e0375d0
	v_fma_f32 v165, |v160|, v161, |v160|
	v_fma_f32 v161, |v160|, s72, v9
	v_fma_f32 v161, |v160|, v161, s73
	v_fma_f32 v161, |v160|, v161, s74
	v_fma_f32 v161, |v160|, v161, s75
	v_fma_f32 v161, |v160|, v161, s76
; DEV unsigned pack2(float a, float b) { float2v v = {a, b}; return __builtin_bit_cast(unsigned, __builtin_convertvector(v, bf16x2v)); }
; DEV float bflo(unsigned u) { return __uint_as_float(u << 16); }
; DEV float bfhi(unsigned u) { return __uint_as_float(u & 0xffff0000u); }
; DEV float gelu_exact(float v) { return 0.5f * v * (1.f + erff(v * 0.7071067811865476f)); }
; DEV void ph_scan2(const Params& p, int item) {
;     ...
; #pragma unroll 8
;   for (int t = 0; t < CHL; ++t) {
;     float4 a = *(const float4*)(p.a_arr + (row0 + t) * 1024 + ch);
;     float4 bb = *(const float4*)(p.b_arr + (row0 + t) * 1024 + ch);
;     u32x2 xg = *(const u32x2*)(p.z + (row0 + t) * ZLD + CXG + ch);
;     H[0] = a.x * H[0] + bb.x; H[1] = a.y * H[1] + bb.y; H[2] = a.z * H[2] + bb.z; H[3] = a.w * H[3] + bb.w;
;     u32x2 pk;
;     pk[0] = pack2(gelu_exact(bflo(xg[0])) * H[0], gelu_exact(bfhi(xg[0])) * H[1]);
;     pk[1] = pack2(gelu_exact(bflo(xg[1])) * H[2], gelu_exact(bfhi(xg[1])) * H[3]);
;     *(u32x2*)(p.orn + (row0 + t) * 1024 + ch) = pk;
;   }
	v_fma_f32 v161, |v160|, v161, s77
	v_fma_f32 v161, |v160|, v161, |v160|
	v_mul_f32_e32 v162, 0xbfb8aa3b, v161
	v_fma_f32 v163, v161, s78, -v162
	v_rndne_f32_e32 v164, v162
	v_fmac_f32_e32 v163, 0xb2a5705f, v161
	v_sub_f32_e32 v162, v162, v164
	v_add_f32_e32 v162, v162, v163
	v_cvt_i32_f32_e32 v163, v164
	v_exp_f32_e32 v162, v162
	v_cmp_nlt_f32_e32 vcc, s79, v161
	v_ldexp_f32 v162, v162, v163
	s_nop 0
	v_cndmask_b32_e32 v162, 0, v162, vcc
	v_cmp_ngt_f32_e32 vcc, s80, v161
	s_nop 1
	v_cndmask_b32_e32 v161, v3, v162, vcc
	v_sub_f32_e32 v166, 1.0, v161
	v_cmp_lt_f32_e64 vcc, |v160|, 1.0
	s_nop 1
	v_cndmask_b32_e32 v165, v166, v165, vcc
	v_bfi_b32 v165, s81, v165, v160
	v_mul_f32_e32 v161, 0.5, v170
	v_add_f32_e32 v165, 1.0, v165
	v_mul_f32_e32 v161, v161, v165
	v_mul_f32_e32 v178, v161, v6
	v_mul_f32_e32 v160, 0x3f3504f3, v171
	v_mul_f32_e32 v161, v160, v160
	v_fmamk_f32 v162, v161, 0xba1345e1, v8
	v_fmaak_f32 v162, v161, v162, 0xbcdac9b8
	v_fmaak_f32 v162, v161, v162, 0x3de703be
	v_fmaak_f32 v162, v161, v162, 0xbec09330
	v_fmaak_f32 v161, v161, v162, 0x3e0375d0
	v_fma_f32 v165, |v160|, v161, |v160|
	v_fma_f32 v161, |v160|, s72, v9
	v_fma_f32 v161, |v160|, v161, s73
	v_fma_f32 v161, |v160|, v161, s74
	v_fma_f32 v161, |v160|, v161, s75
	v_fma_f32 v161, |v160|, v161, s76
	v_fma_f32 v161, |v160|, v161, s77
	v_fma_f32 v161, |v160|, v161, |v160|
	v_mul_f32_e32 v162, 0xbfb8aa3b, v161
	v_fma_f32 v163, v161, s78, -v162
	v_rndne_f32_e32 v164, v162
	v_fmac_f32_e32 v163, 0xb2a5705f, v161
	v_sub_f32_e32 v162, v162, v164
	v_add_f32_e32 v162, v162, v163
	v_cvt_i32_f32_e32 v163, v164
	v_exp_f32_e32 v162, v162
	v_cmp_nlt_f32_e32 vcc, s79, v161
	v_ldexp_f32 v162, v162, v163
	s_nop 0
	v_cndmask_b32_e32 v162, 0, v162, vcc
	v_cmp_ngt_f32_e32 vcc, s80, v161
	s_nop 1
	v_cndmask_b32_e32 v161, v3, v162, vcc
	v_sub_f32_e32 v166, 1.0, v161
	v_cmp_lt_f32_e64 vcc, |v160|, 1.0
	s_nop 1
	v_cndmask_b32_e32 v165, v166, v165, vcc
	v_bfi_b32 v165, s81, v165, v160
	v_mul_f32_e32 v161, 0.5, v171
	v_add_f32_e32 v165, 1.0, v165
	v_mul_f32_e32 v161, v161, v165
	v_mul_f32_e32 v179, v161, v7
	v_cvt_pk_bf16_f32 v180, v176, v177
	v_cvt_pk_bf16_f32 v181, v178, v179
	global_store_dwordx2 v2, v[180:181], s[34:35]
	s_add_u32 s34, s34, 0x800
	s_addc_u32 s35, s35, 0
	s_waitcnt vmcnt(9)
	v_fma_f32 v4, v140, v4, v144
	v_fma_f32 v5, v141, v5, v145
	v_fma_f32 v6, v142, v6, v146
	v_fma_f32 v7, v143, v7, v147
	v_lshlrev_b32_e32 v168, 16, v148
	v_and_b32_e32 v169, 0xffff0000, v148
	v_lshlrev_b32_e32 v170, 16, v149
	v_and_b32_e32 v171, 0xffff0000, v149
	v_mul_f32_e32 v160, 0x3f3504f3, v168
	v_mul_f32_e32 v161, v160, v160
	v_fmamk_f32 v162, v161, 0xba1345e1, v8
	v_fmaak_f32 v162, v161, v162, 0xbcdac9b8
	v_fmaak_f32 v162, v161, v162, 0x3de703be
	v_fmaak_f32 v162, v161, v162, 0xbec09330
	v_fmaak_f32 v161, v161, v162, 0x3e0375d0
	v_fma_f32 v165, |v160|, v161, |v160|
	v_fma_f32 v161, |v160|, s72, v9
	v_fma_f32 v161, |v160|, v161, s73
	v_fma_f32 v161, |v160|, v161, s74
	v_fma_f32 v161, |v160|, v161, s75
	v_fma_f32 v161, |v160|, v161, s76
	v_fma_f32 v161, |v160|, v161, s77
	v_fma_f32 v161, |v160|, v161, |v160|
	v_mul_f32_e32 v162, 0xbfb8aa3b, v161
	v_fma_f32 v163, v161, s78, -v162
	v_rndne_f32_e32 v164, v162
	v_fmac_f32_e32 v163, 0xb2a5705f, v161
	v_sub_f32_e32 v162, v162, v164
	v_add_f32_e32 v162, v162, v163
	v_cvt_i32_f32_e32 v163, v164
	v_exp_f32_e32 v162, v162
	v_cmp_nlt_f32_e32 vcc, s79, v161
	v_ldexp_f32 v162, v162, v163
	s_nop 0
	v_cndmask_b32_e32 v162, 0, v162, vcc
	v_cmp_ngt_f32_e32 vcc, s80, v161
	s_nop 1
	v_cndmask_b32_e32 v161, v3, v162, vcc
	v_sub_f32_e32 v166, 1.0, v161
	v_cmp_lt_f32_e64 vcc, |v160|, 1.0
	s_nop 1
	v_cndmask_b32_e32 v165, v166, v165, vcc
	v_bfi_b32 v165, s81, v165, v160
	v_mul_f32_e32 v161, 0.5, v168
	v_add_f32_e32 v165, 1.0, v165
	v_mul_f32_e32 v161, v161, v165
	v_mul_f32_e32 v176, v161, v4
	v_mul_f32_e32 v160, 0x3f3504f3, v169
	v_mul_f32_e32 v161, v160, v160
	v_fmamk_f32 v162, v161, 0xba1345e1, v8
	v_fmaak_f32 v162, v161, v162, 0xbcdac9b8
	v_fmaak_f32 v162, v161, v162, 0x3de703be
	v_fmaak_f32 v162, v161, v162, 0xbec09330
	v_fmaak_f32 v161, v161, v162, 0x3e0375d0
	v_fma_f32 v165, |v160|, v161, |v160|
	v_fma_f32 v161, |v160|, s72, v9
	v_fma_f32 v161, |v160|, v161, s73
	v_fma_f32 v161, |v160|, v161, s74
	v_fma_f32 v161, |v160|, v161, s75
	v_fma_f32 v161, |v160|, v161, s76
	v_fma_f32 v161, |v160|, v161, s77
	v_fma_f32 v161, |v160|, v161, |v160|
	v_mul_f32_e32 v162, 0xbfb8aa3b, v161
	v_fma_f32 v163, v161, s78, -v162
	v_rndne_f32_e32 v164, v162
	v_fmac_f32_e32 v163, 0xb2a5705f, v161
	v_sub_f32_e32 v162, v162, v164
	v_add_f32_e32 v162, v162, v163
	v_cvt_i32_f32_e32 v163, v164
	v_exp_f32_e32 v162, v162
	v_cmp_nlt_f32_e32 vcc, s79, v161
	v_ldexp_f32 v162, v162, v163
	s_nop 0
	v_cndmask_b32_e32 v162, 0, v162, vcc
	v_cmp_ngt_f32_e32 vcc, s80, v161
	s_nop 1
	v_cndmask_b32_e32 v161, v3, v162, vcc
	v_sub_f32_e32 v166, 1.0, v161
	v_cmp_lt_f32_e64 vcc, |v160|, 1.0
	s_nop 1
	v_cndmask_b32_e32 v165, v166, v165, vcc
	v_bfi_b32 v165, s81, v165, v160
	v_mul_f32_e32 v161, 0.5, v169
	v_add_f32_e32 v165, 1.0, v165
	v_mul_f32_e32 v161, v161, v165
	v_mul_f32_e32 v177, v161, v5
	v_mul_f32_e32 v160, 0x3f3504f3, v170
	v_mul_f32_e32 v161, v160, v160
	v_fmamk_f32 v162, v161, 0xba1345e1, v8
	v_fmaak_f32 v162, v161, v162, 0xbcdac9b8
	v_fmaak_f32 v162, v161, v162, 0x3de703be
	v_fmaak_f32 v162, v161, v162, 0xbec09330
	v_fmaak_f32 v161, v161, v162, 0x3e0375d0
	v_fma_f32 v165, |v160|, v161, |v160|
	v_fma_f32 v161, |v160|, s72, v9
	v_fma_f32 v161, |v160|, v161, s73
	v_fma_f32 v161, |v160|, v161, s74
	v_fma_f32 v161, |v160|, v161, s75
	v_fma_f32 v161, |v160|, v161, s76
	v_fma_f32 v161, |v160|, v161, s77
; DEV unsigned pack2(float a, float b) { float2v v = {a, b}; return __builtin_bit_cast(unsigned, __builtin_convertvector(v, bf16x2v)); }
; DEV float bflo(unsigned u) { return __uint_as_float(u << 16); }
; DEV float bfhi(unsigned u) { return __uint_as_float(u & 0xffff0000u); }
; DEV float gelu_exact(float v) { return 0.5f * v * (1.f + erff(v * 0.7071067811865476f)); }
; DEV void ph_scan2(const Params& p, int item) {
;     ...
; #pragma unroll 8
;   for (int t = 0; t < CHL; ++t) {
;     float4 a = *(const float4*)(p.a_arr + (row0 + t) * 1024 + ch);
;     float4 bb = *(const float4*)(p.b_arr + (row0 + t) * 1024 + ch);
;     u32x2 xg = *(const u32x2*)(p.z + (row0 + t) * ZLD + CXG + ch);
;     H[0] = a.x * H[0] + bb.x; H[1] = a.y * H[1] + bb.y; H[2] = a.z * H[2] + bb.z; H[3] = a.w * H[3] + bb.w;
;     u32x2 pk;
;     pk[0] = pack2(gelu_exact(bflo(xg[0])) * H[0], gelu_exact(bfhi(xg[0])) * H[1]);
;     pk[1] = pack2(gelu_exact(bflo(xg[1])) * H[2], gelu_exact(bfhi(xg[1])) * H[3]);
;     *(u32x2*)(p.orn + (row0 + t) * 1024 + ch) = pk;
;   }
	v_fma_f32 v161, |v160|, v161, |v160|
	v_mul_f32_e32 v162, 0xbfb8aa3b, v161
	v_fma_f32 v163, v161, s78, -v162
	v_rndne_f32_e32 v164, v162
	v_fmac_f32_e32 v163, 0xb2a5705f, v161
	v_sub_f32_e32 v162, v162, v164
	v_add_f32_e32 v162, v162, v163
	v_cvt_i32_f32_e32 v163, v164
	v_exp_f32_e32 v162, v162
	v_cmp_nlt_f32_e32 vcc, s79, v161
	v_ldexp_f32 v162, v162, v163
	s_nop 0
	v_cndmask_b32_e32 v162, 0, v162, vcc
	v_cmp_ngt_f32_e32 vcc, s80, v161
	s_nop 1
	v_cndmask_b32_e32 v161, v3, v162, vcc
	v_sub_f32_e32 v166, 1.0, v161
	v_cmp_lt_f32_e64 vcc, |v160|, 1.0
	s_nop 1
	v_cndmask_b32_e32 v165, v166, v165, vcc
	v_bfi_b32 v165, s81, v165, v160
	v_mul_f32_e32 v161, 0.5, v170
	v_add_f32_e32 v165, 1.0, v165
	v_mul_f32_e32 v161, v161, v165
	v_mul_f32_e32 v178, v161, v6
	v_mul_f32_e32 v160, 0x3f3504f3, v171
	v_mul_f32_e32 v161, v160, v160
	v_fmamk_f32 v162, v161, 0xba1345e1, v8
	v_fmaak_f32 v162, v161, v162, 0xbcdac9b8
	v_fmaak_f32 v162, v161, v162, 0x3de703be
	v_fmaak_f32 v162, v161, v162, 0xbec09330
	v_fmaak_f32 v161, v161, v162, 0x3e0375d0
	v_fma_f32 v165, |v160|, v161, |v160|
	v_fma_f32 v161, |v160|, s72, v9
	v_fma_f32 v161, |v160|, v161, s73
	v_fma_f32 v161, |v160|, v161, s74
	v_fma_f32 v161, |v160|, v161, s75
	v_fma_f32 v161, |v160|, v161, s76
	v_fma_f32 v161, |v160|, v161, s77
	v_fma_f32 v161, |v160|, v161, |v160|
	v_mul_f32_e32 v162, 0xbfb8aa3b, v161
	v_fma_f32 v163, v161, s78, -v162
	v_rndne_f32_e32 v164, v162
	v_fmac_f32_e32 v163, 0xb2a5705f, v161
	v_sub_f32_e32 v162, v162, v164
	v_add_f32_e32 v162, v162, v163
	v_cvt_i32_f32_e32 v163, v164
	v_exp_f32_e32 v162, v162
	v_cmp_nlt_f32_e32 vcc, s79, v161
	v_ldexp_f32 v162, v162, v163
	s_nop 0
	v_cndmask_b32_e32 v162, 0, v162, vcc
	v_cmp_ngt_f32_e32 vcc, s80, v161
	s_nop 1
	v_cndmask_b32_e32 v161, v3, v162, vcc
	v_sub_f32_e32 v166, 1.0, v161
	v_cmp_lt_f32_e64 vcc, |v160|, 1.0
	s_nop 1
	v_cndmask_b32_e32 v165, v166, v165, vcc
	v_bfi_b32 v165, s81, v165, v160
	v_mul_f32_e32 v161, 0.5, v171
	v_add_f32_e32 v165, 1.0, v165
	v_mul_f32_e32 v161, v161, v165
	v_mul_f32_e32 v179, v161, v7
	v_cvt_pk_bf16_f32 v180, v176, v177
	v_cvt_pk_bf16_f32 v181, v178, v179
	global_store_dwordx2 v2, v[180:181], s[34:35]
	s_add_u32 s34, s34, 0x800
	s_addc_u32 s35, s35, 0
	s_waitcnt vmcnt(7)
; DEV unsigned pack2(float a, float b) { float2v v = {a, b}; return __builtin_bit_cast(unsigned, __builtin_convertvector(v, bf16x2v)); }
; DEV float bflo(unsigned u) { return __uint_as_float(u << 16); }
; DEV float bfhi(unsigned u) { return __uint_as_float(u & 0xffff0000u); }
; DEV float gelu_exact(float v) { return 0.5f * v * (1.f + erff(v * 0.7071067811865476f)); }
; DEV void ph_scan2(const Params& p, int item) {
;     ...
;   for (int t = 0; t < CHL; ++t) {
;     float4 a = *(const float4*)(p.a_arr + (row0 + t) * 1024 + ch);
;     float4 bb = *(const float4*)(p.b_arr + (row0 + t) * 1024 + ch);
;     u32x2 xg = *(const u32x2*)(p.z + (row0 + t) * ZLD + CXG + ch);
;     H[0] = a.x * H[0] + bb.x; H[1] = a.y * H[1] + bb.y; H[2] = a.z * H[2] + bb.z; H[3] = a.w * H[3] + bb.w;
;     u32x2 pk;
;     pk[0] = pack2(gelu_exact(bflo(xg[0])) * H[0], gelu_exact(bfhi(xg[0])) * H[1]);
;     pk[1] = pack2(gelu_exact(bflo(xg[1])) * H[2], gelu_exact(bfhi(xg[1])) * H[3]);
;     *(u32x2*)(p.orn + (row0 + t) * 1024 + ch) = pk;
;   }
	v_fma_f32 v4, v150, v4, v154
	v_fma_f32 v5, v151, v5, v155
	v_fma_f32 v6, v152, v6, v156
	v_fma_f32 v7, v153, v7, v157
	v_lshlrev_b32_e32 v168, 16, v158
	v_and_b32_e32 v169, 0xffff0000, v158
	v_lshlrev_b32_e32 v170, 16, v159
	v_and_b32_e32 v171, 0xffff0000, v159
	v_mul_f32_e32 v160, 0x3f3504f3, v168
	v_mul_f32_e32 v161, v160, v160
	v_fmamk_f32 v162, v161, 0xba1345e1, v8
	v_fmaak_f32 v162, v161, v162, 0xbcdac9b8
	v_fmaak_f32 v162, v161, v162, 0x3de703be
	v_fmaak_f32 v162, v161, v162, 0xbec09330
	v_fmaak_f32 v161, v161, v162, 0x3e0375d0
	v_fma_f32 v165, |v160|, v161, |v160|
	v_fma_f32 v161, |v160|, s72, v9
	v_fma_f32 v161, |v160|, v161, s73
	v_fma_f32 v161, |v160|, v161, s74
	v_fma_f32 v161, |v160|, v161, s75
	v_fma_f32 v161, |v160|, v161, s76
	v_fma_f32 v161, |v160|, v161, s77
	v_fma_f32 v161, |v160|, v161, |v160|
	v_mul_f32_e32 v162, 0xbfb8aa3b, v161
	v_fma_f32 v163, v161, s78, -v162
	v_rndne_f32_e32 v164, v162
	v_fmac_f32_e32 v163, 0xb2a5705f, v161
	v_sub_f32_e32 v162, v162, v164
	v_add_f32_e32 v162, v162, v163
	v_cvt_i32_f32_e32 v163, v164
	v_exp_f32_e32 v162, v162
	v_cmp_nlt_f32_e32 vcc, s79, v161
	v_ldexp_f32 v162, v162, v163
	s_nop 0
	v_cndmask_b32_e32 v162, 0, v162, vcc
	v_cmp_ngt_f32_e32 vcc, s80, v161
	s_nop 1
	v_cndmask_b32_e32 v161, v3, v162, vcc
	v_sub_f32_e32 v166, 1.0, v161
	v_cmp_lt_f32_e64 vcc, |v160|, 1.0
	s_nop 1
	v_cndmask_b32_e32 v165, v166, v165, vcc
	v_bfi_b32 v165, s81, v165, v160
	v_mul_f32_e32 v161, 0.5, v168
	v_add_f32_e32 v165, 1.0, v165
	v_mul_f32_e32 v161, v161, v165
	v_mul_f32_e32 v176, v161, v4
	v_mul_f32_e32 v160, 0x3f3504f3, v169
	v_mul_f32_e32 v161, v160, v160
	v_fmamk_f32 v162, v161, 0xba1345e1, v8
	v_fmaak_f32 v162, v161, v162, 0xbcdac9b8
	v_fmaak_f32 v162, v161, v162, 0x3de703be
	v_fmaak_f32 v162, v161, v162, 0xbec09330
	v_fmaak_f32 v161, v161, v162, 0x3e0375d0
	v_fma_f32 v165, |v160|, v161, |v160|
	v_fma_f32 v161, |v160|, s72, v9
	v_fma_f32 v161, |v160|, v161, s73
	v_fma_f32 v161, |v160|, v161, s74
	v_fma_f32 v161, |v160|, v161, s75
	v_fma_f32 v161, |v160|, v161, s76
	v_fma_f32 v161, |v160|, v161, s77
	v_fma_f32 v161, |v160|, v161, |v160|
	v_mul_f32_e32 v162, 0xbfb8aa3b, v161
	v_fma_f32 v163, v161, s78, -v162
	v_rndne_f32_e32 v164, v162
	v_fmac_f32_e32 v163, 0xb2a5705f, v161
	v_sub_f32_e32 v162, v162, v164
	v_add_f32_e32 v162, v162, v163
	v_cvt_i32_f32_e32 v163, v164
	v_exp_f32_e32 v162, v162
	v_cmp_nlt_f32_e32 vcc, s79, v161
	v_ldexp_f32 v162, v162, v163
	s_nop 0
	v_cndmask_b32_e32 v162, 0, v162, vcc
	v_cmp_ngt_f32_e32 vcc, s80, v161
	s_nop 1
	v_cndmask_b32_e32 v161, v3, v162, vcc
	v_sub_f32_e32 v166, 1.0, v161
	v_cmp_lt_f32_e64 vcc, |v160|, 1.0
	s_nop 1
	v_cndmask_b32_e32 v165, v166, v165, vcc
	v_bfi_b32 v165, s81, v165, v160
	v_mul_f32_e32 v161, 0.5, v169
	v_add_f32_e32 v165, 1.0, v165
	v_mul_f32_e32 v161, v161, v165
	v_mul_f32_e32 v177, v161, v5
	v_mul_f32_e32 v160, 0x3f3504f3, v170
	v_mul_f32_e32 v161, v160, v160
	v_fmamk_f32 v162, v161, 0xba1345e1, v8
	v_fmaak_f32 v162, v161, v162, 0xbcdac9b8
	v_fmaak_f32 v162, v161, v162, 0x3de703be
	v_fmaak_f32 v162, v161, v162, 0xbec09330
	v_fmaak_f32 v161, v161, v162, 0x3e0375d0
	v_fma_f32 v165, |v160|, v161, |v160|
	v_fma_f32 v161, |v160|, s72, v9
	v_fma_f32 v161, |v160|, v161, s73
	v_fma_f32 v161, |v160|, v161, s74
	v_fma_f32 v161, |v160|, v161, s75
	v_fma_f32 v161, |v160|, v161, s76
	v_fma_f32 v161, |v160|, v161, s77
	v_fma_f32 v161, |v160|, v161, |v160|
	v_mul_f32_e32 v162, 0xbfb8aa3b, v161
	v_fma_f32 v163, v161, s78, -v162
	v_rndne_f32_e32 v164, v162
	v_fmac_f32_e32 v163, 0xb2a5705f, v161
	v_sub_f32_e32 v162, v162, v164
	v_add_f32_e32 v162, v162, v163
	v_cvt_i32_f32_e32 v163, v164
	v_exp_f32_e32 v162, v162
	v_cmp_nlt_f32_e32 vcc, s79, v161
	v_ldexp_f32 v162, v162, v163
	s_nop 0
	v_cndmask_b32_e32 v162, 0, v162, vcc
	v_cmp_ngt_f32_e32 vcc, s80, v161
	s_nop 1
	v_cndmask_b32_e32 v161, v3, v162, vcc
	v_sub_f32_e32 v166, 1.0, v161
	v_cmp_lt_f32_e64 vcc, |v160|, 1.0
	s_nop 1
	v_cndmask_b32_e32 v165, v166, v165, vcc
	v_bfi_b32 v165, s81, v165, v160
	v_mul_f32_e32 v161, 0.5, v170
	v_add_f32_e32 v165, 1.0, v165
	v_mul_f32_e32 v161, v161, v165
	v_mul_f32_e32 v178, v161, v6
	v_mul_f32_e32 v160, 0x3f3504f3, v171
	v_mul_f32_e32 v161, v160, v160
	v_fmamk_f32 v162, v161, 0xba1345e1, v8
	v_fmaak_f32 v162, v161, v162, 0xbcdac9b8
	v_fmaak_f32 v162, v161, v162, 0x3de703be
	v_fmaak_f32 v162, v161, v162, 0xbec09330
	v_fmaak_f32 v161, v161, v162, 0x3e0375d0
	v_fma_f32 v165, |v160|, v161, |v160|
	v_fma_f32 v161, |v160|, s72, v9
	v_fma_f32 v161, |v160|, v161, s73
	v_fma_f32 v161, |v160|, v161, s74
	v_fma_f32 v161, |v160|, v161, s75
	v_fma_f32 v161, |v160|, v161, s76
	v_fma_f32 v161, |v160|, v161, s77
	v_fma_f32 v161, |v160|, v161, |v160|
	v_mul_f32_e32 v162, 0xbfb8aa3b, v161
	v_fma_f32 v163, v161, s78, -v162
	v_rndne_f32_e32 v164, v162
	v_fmac_f32_e32 v163, 0xb2a5705f, v161
	v_sub_f32_e32 v162, v162, v164
	v_add_f32_e32 v162, v162, v163
	v_cvt_i32_f32_e32 v163, v164
	v_exp_f32_e32 v162, v162
	v_cmp_nlt_f32_e32 vcc, s79, v161
	v_ldexp_f32 v162, v162, v163
	s_nop 0
	v_cndmask_b32_e32 v162, 0, v162, vcc
	v_cmp_ngt_f32_e32 vcc, s80, v161
	s_nop 1
	v_cndmask_b32_e32 v161, v3, v162, vcc
	v_sub_f32_e32 v166, 1.0, v161
	v_cmp_lt_f32_e64 vcc, |v160|, 1.0
	s_nop 1
	v_cndmask_b32_e32 v165, v166, v165, vcc
	v_bfi_b32 v165, s81, v165, v160
	v_mul_f32_e32 v161, 0.5, v171
	v_add_f32_e32 v165, 1.0, v165
	v_mul_f32_e32 v161, v161, v165
	v_mul_f32_e32 v179, v161, v7
	v_cvt_pk_bf16_f32 v180, v176, v177
	v_cvt_pk_bf16_f32 v181, v178, v179
	global_store_dwordx2 v2, v[180:181], s[34:35]
	s_add_u32 s34, s34, 0x800
	s_addc_u32 s35, s35, 0
	s_add_u32 s41, s41, 1
	s_cmp_lt_u32 s41, 4
	s_cbranch_scc1 .Lsc_main
	s_add_i32 s50, s50, s92
	s_cmpk_lt_i32 s50, 0x200
	s_cbranch_scc1 .Lsc_item
	v_readlane_b32 s2, v254, 0
	s_nop 3
	s_cmp_lt_u32 s2, 0x100
	s_cbranch_scc1 .Lp5_resume
